# barrier protocol: non-leader workgroups issue buffer_inv on arrival (overlapped with waiting); XCD leader completes its invalidate before releasing locals
# speedup vs baseline: 1.0031x; 1.0031x over previous
; __device__ __forceinline__ unsigned xb_ld(unsigned* p)              { return __hip_atomic_load(p, __ATOMIC_RELAXED, __HIP_MEMORY_SCOPE_AGENT); }
; __device__ __forceinline__ unsigned xb_add(unsigned* p, unsigned v) { return __hip_atomic_fetch_add(p, v, __ATOMIC_RELAXED, __HIP_MEMORY_SCOPE_AGENT); }
; #define XB_SPIN(cond, bar) do { unsigned _sp = 0; while (cond) { __builtin_amdgcn_s_sleep(1); \
;     if ((++_sp & 255u) == 0u) { if (xb_ld(&(bar)[XB_TMO])) break; if (_sp > XB_SPIN_CAP) { atomicAdd(&(bar)[XB_TMO], 1u); break; } } } } while (0)
; __device__ __forceinline__ void xcd_barrier(const XcdBarrier& b) {
;     ...
;         const unsigned old = xb_add(&bar[XB_XSUB(b.x)], 1u);
;         const unsigned gen = old / nloc;
;         if (old + 1u == (gen + 1u) * nloc) {
;             __builtin_amdgcn_fence(__ATOMIC_RELEASE, "agent");
;             asm volatile("s_waitcnt vmcnt(0)" ::: "memory");
;             const unsigned og = xb_add(&bar[XB_TOP], 1u);
;             const unsigned tg = og / nx;
;             if (og + 1u == (tg + 1u) * nx) xb_add(&bar[XB_TOPGEN], 1u);
;             else XB_SPIN(xb_ld(&bar[XB_TOPGEN]) == tg, bar);
;             __builtin_amdgcn_fence(__ATOMIC_ACQUIRE, "agent");
;             xb_add(&bar[XB_XGEN(b.x)], 1u);
;             asm volatile("s_waitcnt vmcnt(0)" ::: "memory");
;         } else {
;             XB_SPIN(xb_ld(&bar[XB_XGEN(b.x)]) == gen, bar);
;             __builtin_amdgcn_fence(__ATOMIC_ACQUIRE, "agent");
;             asm volatile("s_waitcnt vmcnt(0)" ::: "memory");
;         }
.LBB0_78:
	s_or_b64 exec, exec, s[12:13]
	v_cvt_f32_u32_e32 v4, v2
	s_waitcnt vmcnt(0)
	v_readfirstlane_b32 s3, v3
	v_sub_u32_e32 v3, 0, v2
	v_rcp_iflag_f32_e32 v4, v4
	v_add_u32_e32 v5, s3, v1
	v_mul_f32_e32 v4, 0x4f7ffffe, v4
	v_cvt_u32_f32_e32 v4, v4
	v_mul_lo_u32 v1, v3, v4
	v_mul_hi_u32 v1, v4, v1
	v_add_u32_e32 v1, v4, v1
	v_mul_hi_u32 v1, v5, v1
	v_mul_lo_u32 v3, v1, v2
	v_sub_u32_e32 v3, v5, v3
	v_add_u32_e32 v4, 1, v1
	v_cmp_ge_u32_e32 vcc, v3, v2
	s_nop 1
	v_cndmask_b32_e32 v1, v1, v4, vcc
	v_sub_u32_e32 v4, v3, v2
	v_cndmask_b32_e32 v3, v3, v4, vcc
	v_add_u32_e32 v4, 1, v1
	v_cmp_ge_u32_e32 vcc, v3, v2
	v_add_u32_e32 v3, 1, v5
	s_nop 0
	v_cndmask_b32_e32 v1, v1, v4, vcc
	v_mul_lo_u32 v4, v2, v1
	v_add_u32_e32 v2, v4, v2
	v_cmp_ne_u32_e32 vcc, v3, v2
	s_and_saveexec_b64 s[6:7], vcc
	s_xor_b64 s[10:11], exec, s[6:7]
	s_cbranch_execz .LBB0_92
	buffer_inv sc1
	s_waitcnt lgkmcnt(0)
	v_mov_b32_e32 v0, 0x2000
	global_load_dword v0, v0, s[8:9] offset:1024 sc1
	s_add_u32 s16, s8, 0x2400
	s_addc_u32 s17, s9, 0
	s_waitcnt vmcnt(0)
	v_cmp_eq_u32_e32 vcc, v0, v1
	s_and_saveexec_b64 s[12:13], vcc
	s_cbranch_execz .LBB0_91
	s_add_u32 s14, s70, 0x50200
	s_addc_u32 s15, s71, 0
	s_mov_b32 s3, 1
	s_mov_b64 s[18:19], 0
	v_mov_b32_e32 v0, 0
	s_branch .LBB0_82

; __device__ __forceinline__ unsigned xb_ld(unsigned* p)              { return __hip_atomic_load(p, __ATOMIC_RELAXED, __HIP_MEMORY_SCOPE_AGENT); }
; #define XB_SPIN(cond, bar) do { unsigned _sp = 0; while (cond) { __builtin_amdgcn_s_sleep(1); \
;     if ((++_sp & 255u) == 0u) { if (xb_ld(&(bar)[XB_TMO])) break; if (_sp > XB_SPIN_CAP) { atomicAdd(&(bar)[XB_TMO], 1u); break; } } } } while (0)
; __device__ __forceinline__ void xcd_barrier(const XcdBarrier& b) {
;     ...
;         } else {
;             XB_SPIN(xb_ld(&bar[XB_XGEN(b.x)]) == gen, bar);
;             __builtin_amdgcn_fence(__ATOMIC_ACQUIRE, "agent");
;             asm volatile("s_waitcnt vmcnt(0)" ::: "memory");
;         }
.LBB0_91:
	s_or_b64 exec, exec, s[12:13]
	s_waitcnt vmcnt(0)
	s_waitcnt vmcnt(0)

; __device__ __forceinline__ unsigned xb_ld(unsigned* p)              { return __hip_atomic_load(p, __ATOMIC_RELAXED, __HIP_MEMORY_SCOPE_AGENT); }
; __device__ __forceinline__ unsigned xb_add(unsigned* p, unsigned v) { return __hip_atomic_fetch_add(p, v, __ATOMIC_RELAXED, __HIP_MEMORY_SCOPE_AGENT); }
; #define XB_SPIN(cond, bar) do { unsigned _sp = 0; while (cond) { __builtin_amdgcn_s_sleep(1); \
;     if ((++_sp & 255u) == 0u) { if (xb_ld(&(bar)[XB_TMO])) break; if (_sp > XB_SPIN_CAP) { atomicAdd(&(bar)[XB_TMO], 1u); break; } } } } while (0)
; __device__ __forceinline__ void xcd_barrier(const XcdBarrier& b) {
;     ...
;             __builtin_amdgcn_fence(__ATOMIC_RELEASE, "agent");
;             asm volatile("s_waitcnt vmcnt(0)" ::: "memory");
;             const unsigned og = xb_add(&bar[XB_TOP], 1u);
;             const unsigned tg = og / nx;
;             if (og + 1u == (tg + 1u) * nx) xb_add(&bar[XB_TOPGEN], 1u);
;             else XB_SPIN(xb_ld(&bar[XB_TOPGEN]) == tg, bar);
;             __builtin_amdgcn_fence(__ATOMIC_ACQUIRE, "agent");
;             xb_add(&bar[XB_XGEN(b.x)], 1u);
;             asm volatile("s_waitcnt vmcnt(0)" ::: "memory");
.LBB0_109:
	s_or_b64 exec, exec, s[10:11]
	s_mov_b64 s[10:11], exec
	v_mbcnt_lo_u32_b32 v0, s10, 0
	v_mbcnt_hi_u32_b32 v0, s11, v0
	v_cmp_eq_u32_e32 vcc, 0, v0
	s_waitcnt vmcnt(0)
	buffer_inv sc1
	s_waitcnt vmcnt(0)
	s_and_saveexec_b64 s[12:13], vcc
	s_cbranch_execz .LBB0_111
	s_bcnt1_i32_b64 s3, s[10:11]
	v_mov_b32_e32 v0, 0x2000
	v_mov_b32_e32 v1, s3
	global_atomic_add v0, v1, s[8:9] offset:1024

; __device__ __forceinline__ unsigned xb_ld(unsigned* p)              { return __hip_atomic_load(p, __ATOMIC_RELAXED, __HIP_MEMORY_SCOPE_AGENT); }
; __device__ __forceinline__ unsigned xb_add(unsigned* p, unsigned v) { return __hip_atomic_fetch_add(p, v, __ATOMIC_RELAXED, __HIP_MEMORY_SCOPE_AGENT); }
; #define XB_SPIN(cond, bar) do { unsigned _sp = 0; while (cond) { __builtin_amdgcn_s_sleep(1); \
;     if ((++_sp & 255u) == 0u) { if (xb_ld(&(bar)[XB_TMO])) break; if (_sp > XB_SPIN_CAP) { atomicAdd(&(bar)[XB_TMO], 1u); break; } } } } while (0)
; __device__ __forceinline__ void xcd_barrier(const XcdBarrier& b) {
;     ...
;         const unsigned old = xb_add(&bar[XB_XSUB(b.x)], 1u);
;         const unsigned gen = old / nloc;
;         if (old + 1u == (gen + 1u) * nloc) {
;             __builtin_amdgcn_fence(__ATOMIC_RELEASE, "agent");
;             asm volatile("s_waitcnt vmcnt(0)" ::: "memory");
;             const unsigned og = xb_add(&bar[XB_TOP], 1u);
;             const unsigned tg = og / nx;
;             if (og + 1u == (tg + 1u) * nx) xb_add(&bar[XB_TOPGEN], 1u);
;             else XB_SPIN(xb_ld(&bar[XB_TOPGEN]) == tg, bar);
;             __builtin_amdgcn_fence(__ATOMIC_ACQUIRE, "agent");
;             xb_add(&bar[XB_XGEN(b.x)], 1u);
;             asm volatile("s_waitcnt vmcnt(0)" ::: "memory");
;         } else {
;             XB_SPIN(xb_ld(&bar[XB_XGEN(b.x)]) == gen, bar);
;             __builtin_amdgcn_fence(__ATOMIC_ACQUIRE, "agent");
;             asm volatile("s_waitcnt vmcnt(0)" ::: "memory");
;         }
.LBB0_164:
	s_or_b64 exec, exec, s[30:31]
	v_cvt_f32_u32_e32 v4, v2
	s_waitcnt vmcnt(0)
	v_readfirstlane_b32 s3, v3
	v_sub_u32_e32 v3, 0, v2
	v_rcp_iflag_f32_e32 v4, v4
	v_add_u32_e32 v5, s3, v1
	v_mul_f32_e32 v4, 0x4f7ffffe, v4
	v_cvt_u32_f32_e32 v4, v4
	v_mul_lo_u32 v1, v3, v4
	v_mul_hi_u32 v1, v4, v1
	v_add_u32_e32 v1, v4, v1
	v_mul_hi_u32 v1, v5, v1
	v_mul_lo_u32 v3, v1, v2
	v_sub_u32_e32 v3, v5, v3
	v_add_u32_e32 v4, 1, v1
	v_cmp_ge_u32_e32 vcc, v3, v2
	s_nop 1
	v_cndmask_b32_e32 v1, v1, v4, vcc
	v_sub_u32_e32 v4, v3, v2
	v_cndmask_b32_e32 v3, v3, v4, vcc
	v_add_u32_e32 v4, 1, v1
	v_cmp_ge_u32_e32 vcc, v3, v2
	v_add_u32_e32 v3, 1, v5
	s_nop 0
	v_cndmask_b32_e32 v1, v1, v4, vcc
	v_mul_lo_u32 v4, v2, v1
	v_add_u32_e32 v2, v4, v2
	v_cmp_ne_u32_e32 vcc, v3, v2
	s_and_saveexec_b64 s[6:7], vcc
	s_xor_b64 s[10:11], exec, s[6:7]
	s_cbranch_execz .LBB0_178
	buffer_inv sc1
	s_waitcnt lgkmcnt(0)
	v_mov_b32_e32 v0, 0x2000
	global_load_dword v0, v0, s[8:9] offset:1024 sc1
	s_add_u32 s54, s8, 0x2400
	s_addc_u32 s55, s9, 0
	s_waitcnt vmcnt(0)
	v_cmp_eq_u32_e32 vcc, v0, v1
	s_and_saveexec_b64 s[30:31], vcc
	s_cbranch_execz .LBB0_177
	s_add_u32 s34, s70, 0x50200
	s_addc_u32 s35, s71, 0
	s_mov_b32 s3, 1
	s_mov_b64 s[58:59], 0
	v_mov_b32_e32 v0, 0
	s_branch .LBB0_168

; __device__ __forceinline__ unsigned xb_ld(unsigned* p)              { return __hip_atomic_load(p, __ATOMIC_RELAXED, __HIP_MEMORY_SCOPE_AGENT); }
; #define XB_SPIN(cond, bar) do { unsigned _sp = 0; while (cond) { __builtin_amdgcn_s_sleep(1); \
;     if ((++_sp & 255u) == 0u) { if (xb_ld(&(bar)[XB_TMO])) break; if (_sp > XB_SPIN_CAP) { atomicAdd(&(bar)[XB_TMO], 1u); break; } } } } while (0)
; __device__ __forceinline__ void xcd_barrier(const XcdBarrier& b) {
;     ...
;         } else {
;             XB_SPIN(xb_ld(&bar[XB_XGEN(b.x)]) == gen, bar);
;             __builtin_amdgcn_fence(__ATOMIC_ACQUIRE, "agent");
;             asm volatile("s_waitcnt vmcnt(0)" ::: "memory");
;         }
.LBB0_177:
	s_or_b64 exec, exec, s[30:31]
	s_waitcnt vmcnt(0)
	s_waitcnt vmcnt(0)

; __device__ __forceinline__ unsigned xb_ld(unsigned* p)              { return __hip_atomic_load(p, __ATOMIC_RELAXED, __HIP_MEMORY_SCOPE_AGENT); }
; __device__ __forceinline__ unsigned xb_add(unsigned* p, unsigned v) { return __hip_atomic_fetch_add(p, v, __ATOMIC_RELAXED, __HIP_MEMORY_SCOPE_AGENT); }
; #define XB_SPIN(cond, bar) do { unsigned _sp = 0; while (cond) { __builtin_amdgcn_s_sleep(1); \
;     if ((++_sp & 255u) == 0u) { if (xb_ld(&(bar)[XB_TMO])) break; if (_sp > XB_SPIN_CAP) { atomicAdd(&(bar)[XB_TMO], 1u); break; } } } } while (0)
; __device__ __forceinline__ void xcd_barrier(const XcdBarrier& b) {
;     ...
;             __builtin_amdgcn_fence(__ATOMIC_RELEASE, "agent");
;             asm volatile("s_waitcnt vmcnt(0)" ::: "memory");
;             const unsigned og = xb_add(&bar[XB_TOP], 1u);
;             const unsigned tg = og / nx;
;             if (og + 1u == (tg + 1u) * nx) xb_add(&bar[XB_TOPGEN], 1u);
;             else XB_SPIN(xb_ld(&bar[XB_TOPGEN]) == tg, bar);
;             __builtin_amdgcn_fence(__ATOMIC_ACQUIRE, "agent");
;             xb_add(&bar[XB_XGEN(b.x)], 1u);
;             asm volatile("s_waitcnt vmcnt(0)" ::: "memory");
.LBB0_195:
	s_or_b64 exec, exec, s[10:11]
	s_mov_b64 s[10:11], exec
	v_mbcnt_lo_u32_b32 v0, s10, 0
	v_mbcnt_hi_u32_b32 v0, s11, v0
	v_cmp_eq_u32_e32 vcc, 0, v0
	s_waitcnt vmcnt(0)
	buffer_inv sc1
	s_waitcnt vmcnt(0)
	s_and_saveexec_b64 s[30:31], vcc
	s_cbranch_execz .LBB0_197
	s_bcnt1_i32_b64 s3, s[10:11]
	v_mov_b32_e32 v0, 0x2000
	v_mov_b32_e32 v1, s3
	global_atomic_add v0, v1, s[8:9] offset:1024

; __device__ __forceinline__ unsigned xb_ld(unsigned* p)              { return __hip_atomic_load(p, __ATOMIC_RELAXED, __HIP_MEMORY_SCOPE_AGENT); }
; __device__ __forceinline__ unsigned xb_add(unsigned* p, unsigned v) { return __hip_atomic_fetch_add(p, v, __ATOMIC_RELAXED, __HIP_MEMORY_SCOPE_AGENT); }
; #define XB_SPIN(cond, bar) do { unsigned _sp = 0; while (cond) { __builtin_amdgcn_s_sleep(1); \
;     if ((++_sp & 255u) == 0u) { if (xb_ld(&(bar)[XB_TMO])) break; if (_sp > XB_SPIN_CAP) { atomicAdd(&(bar)[XB_TMO], 1u); break; } } } } while (0)
; __device__ __forceinline__ void xcd_barrier(const XcdBarrier& b) {
;     ...
;         const unsigned old = xb_add(&bar[XB_XSUB(b.x)], 1u);
;         const unsigned gen = old / nloc;
;         if (old + 1u == (gen + 1u) * nloc) {
;             __builtin_amdgcn_fence(__ATOMIC_RELEASE, "agent");
;             asm volatile("s_waitcnt vmcnt(0)" ::: "memory");
;             const unsigned og = xb_add(&bar[XB_TOP], 1u);
;             const unsigned tg = og / nx;
;             if (og + 1u == (tg + 1u) * nx) xb_add(&bar[XB_TOPGEN], 1u);
;             else XB_SPIN(xb_ld(&bar[XB_TOPGEN]) == tg, bar);
;             __builtin_amdgcn_fence(__ATOMIC_ACQUIRE, "agent");
;             xb_add(&bar[XB_XGEN(b.x)], 1u);
;             asm volatile("s_waitcnt vmcnt(0)" ::: "memory");
;         } else {
;             XB_SPIN(xb_ld(&bar[XB_XGEN(b.x)]) == gen, bar);
;             __builtin_amdgcn_fence(__ATOMIC_ACQUIRE, "agent");
;             asm volatile("s_waitcnt vmcnt(0)" ::: "memory");
;         }
.LBB0_220:
	s_or_b64 exec, exec, s[10:11]
	v_cvt_f32_u32_e32 v4, v2
	s_waitcnt vmcnt(0)
	v_readfirstlane_b32 s3, v3
	v_sub_u32_e32 v3, 0, v2
	v_rcp_iflag_f32_e32 v4, v4
	v_add_u32_e32 v5, s3, v1
	v_mul_f32_e32 v4, 0x4f7ffffe, v4
	v_cvt_u32_f32_e32 v4, v4
	v_mul_lo_u32 v1, v3, v4
	v_mul_hi_u32 v1, v4, v1
	v_add_u32_e32 v1, v4, v1
	v_mul_hi_u32 v1, v5, v1
	v_mul_lo_u32 v3, v1, v2
	v_sub_u32_e32 v3, v5, v3
	v_add_u32_e32 v4, 1, v1
	v_cmp_ge_u32_e32 vcc, v3, v2
	s_nop 1
	v_cndmask_b32_e32 v1, v1, v4, vcc
	v_sub_u32_e32 v4, v3, v2
	v_cndmask_b32_e32 v3, v3, v4, vcc
	v_add_u32_e32 v4, 1, v1
	v_cmp_ge_u32_e32 vcc, v3, v2
	v_add_u32_e32 v3, 1, v5
	s_nop 0
	v_cndmask_b32_e32 v1, v1, v4, vcc
	v_mul_lo_u32 v4, v2, v1
	v_add_u32_e32 v2, v4, v2
	v_cmp_ne_u32_e32 vcc, v3, v2
	s_and_saveexec_b64 s[6:7], vcc
	s_xor_b64 s[8:9], exec, s[6:7]
	s_cbranch_execz .LBB0_234
	buffer_inv sc1
	s_waitcnt lgkmcnt(0)
	v_mov_b32_e32 v0, 0x2000
	global_load_dword v0, v0, s[4:5] offset:1024 sc1
	s_add_u32 s34, s4, 0x2400
	s_addc_u32 s35, s5, 0
	s_waitcnt vmcnt(0)
	v_cmp_eq_u32_e32 vcc, v0, v1
	s_and_saveexec_b64 s[10:11], vcc
	s_cbranch_execz .LBB0_233
	s_add_u32 s30, s70, 0x50200
	s_addc_u32 s31, s71, 0
	s_mov_b32 s3, 1
	s_mov_b64 s[54:55], 0
	v_mov_b32_e32 v0, 0
	s_branch .LBB0_224

; __device__ __forceinline__ unsigned xb_ld(unsigned* p)              { return __hip_atomic_load(p, __ATOMIC_RELAXED, __HIP_MEMORY_SCOPE_AGENT); }
; #define XB_SPIN(cond, bar) do { unsigned _sp = 0; while (cond) { __builtin_amdgcn_s_sleep(1); \
;     if ((++_sp & 255u) == 0u) { if (xb_ld(&(bar)[XB_TMO])) break; if (_sp > XB_SPIN_CAP) { atomicAdd(&(bar)[XB_TMO], 1u); break; } } } } while (0)
; __device__ __forceinline__ void xcd_barrier(const XcdBarrier& b) {
;     ...
;         } else {
;             XB_SPIN(xb_ld(&bar[XB_XGEN(b.x)]) == gen, bar);
;             __builtin_amdgcn_fence(__ATOMIC_ACQUIRE, "agent");
;             asm volatile("s_waitcnt vmcnt(0)" ::: "memory");
;         }
.LBB0_233:
	s_or_b64 exec, exec, s[10:11]
	s_waitcnt vmcnt(0)
	s_waitcnt vmcnt(0)

; __device__ __forceinline__ unsigned xb_ld(unsigned* p)              { return __hip_atomic_load(p, __ATOMIC_RELAXED, __HIP_MEMORY_SCOPE_AGENT); }
; __device__ __forceinline__ unsigned xb_add(unsigned* p, unsigned v) { return __hip_atomic_fetch_add(p, v, __ATOMIC_RELAXED, __HIP_MEMORY_SCOPE_AGENT); }
; #define XB_SPIN(cond, bar) do { unsigned _sp = 0; while (cond) { __builtin_amdgcn_s_sleep(1); \
;     if ((++_sp & 255u) == 0u) { if (xb_ld(&(bar)[XB_TMO])) break; if (_sp > XB_SPIN_CAP) { atomicAdd(&(bar)[XB_TMO], 1u); break; } } } } while (0)
; __device__ __forceinline__ void xcd_barrier(const XcdBarrier& b) {
;     ...
;             __builtin_amdgcn_fence(__ATOMIC_RELEASE, "agent");
;             asm volatile("s_waitcnt vmcnt(0)" ::: "memory");
;             const unsigned og = xb_add(&bar[XB_TOP], 1u);
;             const unsigned tg = og / nx;
;             if (og + 1u == (tg + 1u) * nx) xb_add(&bar[XB_TOPGEN], 1u);
;             else XB_SPIN(xb_ld(&bar[XB_TOPGEN]) == tg, bar);
;             __builtin_amdgcn_fence(__ATOMIC_ACQUIRE, "agent");
;             xb_add(&bar[XB_XGEN(b.x)], 1u);
;             asm volatile("s_waitcnt vmcnt(0)" ::: "memory");
.LBB0_251:
	s_or_b64 exec, exec, s[8:9]
	s_mov_b64 s[8:9], exec
	v_mbcnt_lo_u32_b32 v0, s8, 0
	v_mbcnt_hi_u32_b32 v0, s9, v0
	v_cmp_eq_u32_e32 vcc, 0, v0
	s_waitcnt vmcnt(0)
	buffer_inv sc1
	s_waitcnt vmcnt(0)
	s_and_saveexec_b64 s[10:11], vcc
	s_cbranch_execz .LBB0_253
	s_bcnt1_i32_b64 s3, s[8:9]
	v_mov_b32_e32 v0, 0x2000
	v_mov_b32_e32 v1, s3
	global_atomic_add v0, v1, s[4:5] offset:1024

; __device__ __forceinline__ unsigned xb_ld(unsigned* p)              { return __hip_atomic_load(p, __ATOMIC_RELAXED, __HIP_MEMORY_SCOPE_AGENT); }
; __device__ __forceinline__ unsigned xb_add(unsigned* p, unsigned v) { return __hip_atomic_fetch_add(p, v, __ATOMIC_RELAXED, __HIP_MEMORY_SCOPE_AGENT); }
; #define XB_SPIN(cond, bar) do { unsigned _sp = 0; while (cond) { __builtin_amdgcn_s_sleep(1); \
;     if ((++_sp & 255u) == 0u) { if (xb_ld(&(bar)[XB_TMO])) break; if (_sp > XB_SPIN_CAP) { atomicAdd(&(bar)[XB_TMO], 1u); break; } } } } while (0)
; __device__ __forceinline__ void xcd_barrier(const XcdBarrier& b) {
;     ...
;         const unsigned old = xb_add(&bar[XB_XSUB(b.x)], 1u);
;         const unsigned gen = old / nloc;
;         if (old + 1u == (gen + 1u) * nloc) {
;             __builtin_amdgcn_fence(__ATOMIC_RELEASE, "agent");
;             asm volatile("s_waitcnt vmcnt(0)" ::: "memory");
;             const unsigned og = xb_add(&bar[XB_TOP], 1u);
;             const unsigned tg = og / nx;
;             if (og + 1u == (tg + 1u) * nx) xb_add(&bar[XB_TOPGEN], 1u);
;             else XB_SPIN(xb_ld(&bar[XB_TOPGEN]) == tg, bar);
;             __builtin_amdgcn_fence(__ATOMIC_ACQUIRE, "agent");
;             xb_add(&bar[XB_XGEN(b.x)], 1u);
;             asm volatile("s_waitcnt vmcnt(0)" ::: "memory");
;         } else {
;             XB_SPIN(xb_ld(&bar[XB_XGEN(b.x)]) == gen, bar);
;             __builtin_amdgcn_fence(__ATOMIC_ACQUIRE, "agent");
;             asm volatile("s_waitcnt vmcnt(0)" ::: "memory");
;         }
.LBB0_756:
	s_or_b64 exec, exec, s[10:11]
	v_cvt_f32_u32_e32 v4, v2
	s_waitcnt vmcnt(0)
	v_readfirstlane_b32 s2, v3
	v_sub_u32_e32 v3, 0, v2
	v_rcp_iflag_f32_e32 v4, v4
	v_add_u32_e32 v5, s2, v1
	v_mul_f32_e32 v4, 0x4f7ffffe, v4
	v_cvt_u32_f32_e32 v4, v4
	v_mul_lo_u32 v1, v3, v4
	v_mul_hi_u32 v1, v4, v1
	v_add_u32_e32 v1, v4, v1
	v_mul_hi_u32 v1, v5, v1
	v_mul_lo_u32 v3, v1, v2
	v_sub_u32_e32 v3, v5, v3
	v_add_u32_e32 v4, 1, v1
	v_cmp_ge_u32_e32 vcc, v3, v2
	s_nop 1
	v_cndmask_b32_e32 v1, v1, v4, vcc
	v_sub_u32_e32 v4, v3, v2
	v_cndmask_b32_e32 v3, v3, v4, vcc
	v_add_u32_e32 v4, 1, v1
	v_cmp_ge_u32_e32 vcc, v3, v2
	v_add_u32_e32 v3, 1, v5
	s_nop 0
	v_cndmask_b32_e32 v1, v1, v4, vcc
	v_mul_lo_u32 v4, v2, v1
	v_add_u32_e32 v2, v4, v2
	v_cmp_ne_u32_e32 vcc, v3, v2
	s_and_saveexec_b64 s[6:7], vcc
	s_xor_b64 s[8:9], exec, s[6:7]
	s_cbranch_execz .LBB0_770
	buffer_inv sc1
	s_waitcnt lgkmcnt(0)
	v_mov_b32_e32 v0, 0x2000
	global_load_dword v0, v0, s[4:5] offset:1024 sc1
	s_add_u32 s34, s4, 0x2400
	s_addc_u32 s35, s5, 0
	s_waitcnt vmcnt(0)
	v_cmp_eq_u32_e32 vcc, v0, v1
	s_and_saveexec_b64 s[10:11], vcc
	s_cbranch_execz .LBB0_769
	s_add_u32 s30, s70, 0x50200
	s_addc_u32 s31, s71, 0
	s_mov_b32 s3, 1
	s_mov_b64 s[52:53], 0
	v_mov_b32_e32 v0, 0
	s_branch .LBB0_760

; __device__ __forceinline__ unsigned xb_ld(unsigned* p)              { return __hip_atomic_load(p, __ATOMIC_RELAXED, __HIP_MEMORY_SCOPE_AGENT); }
; __device__ __forceinline__ unsigned xb_add(unsigned* p, unsigned v) { return __hip_atomic_fetch_add(p, v, __ATOMIC_RELAXED, __HIP_MEMORY_SCOPE_AGENT); }
; #define XB_SPIN(cond, bar) do { unsigned _sp = 0; while (cond) { __builtin_amdgcn_s_sleep(1); \
;     if ((++_sp & 255u) == 0u) { if (xb_ld(&(bar)[XB_TMO])) break; if (_sp > XB_SPIN_CAP) { atomicAdd(&(bar)[XB_TMO], 1u); break; } } } } while (0)
; __device__ __forceinline__ void xcd_barrier(const XcdBarrier& b) {
;     ...
;             __builtin_amdgcn_fence(__ATOMIC_RELEASE, "agent");
;             asm volatile("s_waitcnt vmcnt(0)" ::: "memory");
;             const unsigned og = xb_add(&bar[XB_TOP], 1u);
;             const unsigned tg = og / nx;
;             if (og + 1u == (tg + 1u) * nx) xb_add(&bar[XB_TOPGEN], 1u);
;             else XB_SPIN(xb_ld(&bar[XB_TOPGEN]) == tg, bar);
;             __builtin_amdgcn_fence(__ATOMIC_ACQUIRE, "agent");
;             xb_add(&bar[XB_XGEN(b.x)], 1u);
;             asm volatile("s_waitcnt vmcnt(0)" ::: "memory");
.LBB0_787:
	s_or_b64 exec, exec, s[8:9]
	s_mov_b64 s[8:9], exec
	v_mbcnt_lo_u32_b32 v0, s8, 0
	v_mbcnt_hi_u32_b32 v0, s9, v0
	v_cmp_eq_u32_e32 vcc, 0, v0
	s_waitcnt vmcnt(0)
	buffer_inv sc1
	s_waitcnt vmcnt(0)
	s_and_saveexec_b64 s[10:11], vcc
	s_cbranch_execz .LBB0_789
	s_bcnt1_i32_b64 s2, s[8:9]
	v_mov_b32_e32 v0, 0x2000
	v_mov_b32_e32 v1, s2
	global_atomic_add v0, v1, s[4:5] offset:1024

; __device__ __forceinline__ unsigned xb_ld(unsigned* p)              { return __hip_atomic_load(p, __ATOMIC_RELAXED, __HIP_MEMORY_SCOPE_AGENT); }
; __device__ __forceinline__ unsigned xb_add(unsigned* p, unsigned v) { return __hip_atomic_fetch_add(p, v, __ATOMIC_RELAXED, __HIP_MEMORY_SCOPE_AGENT); }
; #define XB_SPIN(cond, bar) do { unsigned _sp = 0; while (cond) { __builtin_amdgcn_s_sleep(1); \
;     if ((++_sp & 255u) == 0u) { if (xb_ld(&(bar)[XB_TMO])) break; if (_sp > XB_SPIN_CAP) { atomicAdd(&(bar)[XB_TMO], 1u); break; } } } } while (0)
; __device__ __forceinline__ void xcd_barrier(const XcdBarrier& b) {
;     ...
;         const unsigned old = xb_add(&bar[XB_XSUB(b.x)], 1u);
;         const unsigned gen = old / nloc;
;         if (old + 1u == (gen + 1u) * nloc) {
;             __builtin_amdgcn_fence(__ATOMIC_RELEASE, "agent");
;             asm volatile("s_waitcnt vmcnt(0)" ::: "memory");
;             const unsigned og = xb_add(&bar[XB_TOP], 1u);
;             const unsigned tg = og / nx;
;             if (og + 1u == (tg + 1u) * nx) xb_add(&bar[XB_TOPGEN], 1u);
;             else XB_SPIN(xb_ld(&bar[XB_TOPGEN]) == tg, bar);
;             __builtin_amdgcn_fence(__ATOMIC_ACQUIRE, "agent");
;             xb_add(&bar[XB_XGEN(b.x)], 1u);
;             asm volatile("s_waitcnt vmcnt(0)" ::: "memory");
;         } else {
;             XB_SPIN(xb_ld(&bar[XB_XGEN(b.x)]) == gen, bar);
;             __builtin_amdgcn_fence(__ATOMIC_ACQUIRE, "agent");
;             asm volatile("s_waitcnt vmcnt(0)" ::: "memory");
;         }
.LBB0_1088:
	s_or_b64 exec, exec, s[10:11]
	v_cvt_f32_u32_e32 v4, v2
	s_waitcnt vmcnt(0)
	v_readfirstlane_b32 s2, v3
	v_sub_u32_e32 v3, 0, v2
	v_rcp_iflag_f32_e32 v4, v4
	v_add_u32_e32 v5, s2, v1
	v_mul_f32_e32 v4, 0x4f7ffffe, v4
	v_cvt_u32_f32_e32 v4, v4
	v_mul_lo_u32 v1, v3, v4
	v_mul_hi_u32 v1, v4, v1
	v_add_u32_e32 v1, v4, v1
	v_mul_hi_u32 v1, v5, v1
	v_mul_lo_u32 v3, v1, v2
	v_sub_u32_e32 v3, v5, v3
	v_add_u32_e32 v4, 1, v1
	v_cmp_ge_u32_e32 vcc, v3, v2
	s_nop 1
	v_cndmask_b32_e32 v1, v1, v4, vcc
	v_sub_u32_e32 v4, v3, v2
	v_cndmask_b32_e32 v3, v3, v4, vcc
	v_add_u32_e32 v4, 1, v1
	v_cmp_ge_u32_e32 vcc, v3, v2
	v_add_u32_e32 v3, 1, v5
	s_nop 0
	v_cndmask_b32_e32 v1, v1, v4, vcc
	v_mul_lo_u32 v4, v2, v1
	v_add_u32_e32 v2, v4, v2
	v_cmp_ne_u32_e32 vcc, v3, v2
	s_and_saveexec_b64 s[6:7], vcc
	s_xor_b64 s[8:9], exec, s[6:7]
	s_cbranch_execz .LBB0_1102
	buffer_inv sc1
	s_waitcnt lgkmcnt(0)
	v_mov_b32_e32 v0, 0x2000
	global_load_dword v0, v0, s[4:5] offset:1024 sc1
	s_add_u32 s34, s4, 0x2400
	s_addc_u32 s35, s5, 0
	s_waitcnt vmcnt(0)
	v_cmp_eq_u32_e32 vcc, v0, v1
	s_and_saveexec_b64 s[10:11], vcc
	s_cbranch_execz .LBB0_1101
	s_add_u32 s30, s70, 0x50200
	s_addc_u32 s31, s71, 0
	s_mov_b32 s3, 1
	s_mov_b64 s[42:43], 0
	v_mov_b32_e32 v0, 0
	s_branch .LBB0_1092

; __device__ __forceinline__ unsigned xb_ld(unsigned* p)              { return __hip_atomic_load(p, __ATOMIC_RELAXED, __HIP_MEMORY_SCOPE_AGENT); }
; __device__ __forceinline__ unsigned xb_add(unsigned* p, unsigned v) { return __hip_atomic_fetch_add(p, v, __ATOMIC_RELAXED, __HIP_MEMORY_SCOPE_AGENT); }
; #define XB_SPIN(cond, bar) do { unsigned _sp = 0; while (cond) { __builtin_amdgcn_s_sleep(1); \
;     if ((++_sp & 255u) == 0u) { if (xb_ld(&(bar)[XB_TMO])) break; if (_sp > XB_SPIN_CAP) { atomicAdd(&(bar)[XB_TMO], 1u); break; } } } } while (0)
; __device__ __forceinline__ void xcd_barrier(const XcdBarrier& b) {
;     ...
;         const unsigned old = xb_add(&bar[XB_XSUB(b.x)], 1u);
;         const unsigned gen = old / nloc;
;         if (old + 1u == (gen + 1u) * nloc) {
;             __builtin_amdgcn_fence(__ATOMIC_RELEASE, "agent");
;             asm volatile("s_waitcnt vmcnt(0)" ::: "memory");
;             const unsigned og = xb_add(&bar[XB_TOP], 1u);
;             const unsigned tg = og / nx;
;             if (og + 1u == (tg + 1u) * nx) xb_add(&bar[XB_TOPGEN], 1u);
;             else XB_SPIN(xb_ld(&bar[XB_TOPGEN]) == tg, bar);
;             __builtin_amdgcn_fence(__ATOMIC_ACQUIRE, "agent");
;             xb_add(&bar[XB_XGEN(b.x)], 1u);
;             asm volatile("s_waitcnt vmcnt(0)" ::: "memory");
;         } else {
;             XB_SPIN(xb_ld(&bar[XB_XGEN(b.x)]) == gen, bar);
.LBB0_1228:
	s_or_b64 exec, exec, s[30:31]
	v_cvt_f32_u32_e32 v4, v2
	s_waitcnt vmcnt(0)
	v_readfirstlane_b32 s2, v3
	v_sub_u32_e32 v3, 0, v2
	v_rcp_iflag_f32_e32 v4, v4
	v_add_u32_e32 v5, s2, v1
	v_mul_f32_e32 v4, 0x4f7ffffe, v4
	v_cvt_u32_f32_e32 v4, v4
	v_mul_lo_u32 v1, v3, v4
	v_mul_hi_u32 v1, v4, v1
	v_add_u32_e32 v1, v4, v1
	v_mul_hi_u32 v1, v5, v1
	v_mul_lo_u32 v3, v1, v2
	v_sub_u32_e32 v3, v5, v3
	v_add_u32_e32 v4, 1, v1
	v_cmp_ge_u32_e32 vcc, v3, v2
	s_nop 1
	v_cndmask_b32_e32 v1, v1, v4, vcc
	v_sub_u32_e32 v4, v3, v2
	v_cndmask_b32_e32 v3, v3, v4, vcc
	v_add_u32_e32 v4, 1, v1
	v_cmp_ge_u32_e32 vcc, v3, v2
	v_add_u32_e32 v3, 1, v5
	s_nop 0
	v_cndmask_b32_e32 v1, v1, v4, vcc
	v_mul_lo_u32 v4, v2, v1
	v_add_u32_e32 v2, v4, v2
	v_cmp_ne_u32_e32 vcc, v3, v2
	s_and_saveexec_b64 s[6:7], vcc
	s_xor_b64 s[10:11], exec, s[6:7]
	s_cbranch_execz .LBB0_1242
	buffer_inv sc1
	s_waitcnt lgkmcnt(0)
	v_mov_b32_e32 v0, 0x2000
	global_load_dword v0, v0, s[8:9] offset:1024 sc1
	s_add_u32 s42, s8, 0x2400
	s_addc_u32 s43, s9, 0
	s_waitcnt vmcnt(0)
	v_cmp_eq_u32_e32 vcc, v0, v1
	s_and_saveexec_b64 s[30:31], vcc
	s_cbranch_execz .LBB0_1241
	s_add_u32 s34, s70, 0x50200
	s_addc_u32 s35, s71, 0
	s_mov_b32 s3, 1
	s_mov_b64 s[46:47], 0
	v_mov_b32_e32 v0, 0
	s_branch .LBB0_1232

; __device__ __forceinline__ unsigned xb_ld(unsigned* p)              { return __hip_atomic_load(p, __ATOMIC_RELAXED, __HIP_MEMORY_SCOPE_AGENT); }
; __device__ __forceinline__ unsigned xb_add(unsigned* p, unsigned v) { return __hip_atomic_fetch_add(p, v, __ATOMIC_RELAXED, __HIP_MEMORY_SCOPE_AGENT); }
; #define XB_SPIN(cond, bar) do { unsigned _sp = 0; while (cond) { __builtin_amdgcn_s_sleep(1); \
;     if ((++_sp & 255u) == 0u) { if (xb_ld(&(bar)[XB_TMO])) break; if (_sp > XB_SPIN_CAP) { atomicAdd(&(bar)[XB_TMO], 1u); break; } } } } while (0)
; __device__ __forceinline__ void xcd_barrier(const XcdBarrier& b) {
;     ...
;             __builtin_amdgcn_fence(__ATOMIC_RELEASE, "agent");
;             asm volatile("s_waitcnt vmcnt(0)" ::: "memory");
;             const unsigned og = xb_add(&bar[XB_TOP], 1u);
;             const unsigned tg = og / nx;
;             if (og + 1u == (tg + 1u) * nx) xb_add(&bar[XB_TOPGEN], 1u);
;             else XB_SPIN(xb_ld(&bar[XB_TOPGEN]) == tg, bar);
;             __builtin_amdgcn_fence(__ATOMIC_ACQUIRE, "agent");
;             xb_add(&bar[XB_XGEN(b.x)], 1u);
;             asm volatile("s_waitcnt vmcnt(0)" ::: "memory");
.LBB0_1259:
	s_or_b64 exec, exec, s[10:11]
	s_mov_b64 s[10:11], exec
	v_mbcnt_lo_u32_b32 v0, s10, 0
	v_mbcnt_hi_u32_b32 v0, s11, v0
	v_cmp_eq_u32_e32 vcc, 0, v0
	s_waitcnt vmcnt(0)
	buffer_inv sc1
	s_waitcnt vmcnt(0)
	s_and_saveexec_b64 s[30:31], vcc
	s_cbranch_execz .LBB0_1261
	s_bcnt1_i32_b64 s2, s[10:11]
	v_mov_b32_e32 v0, 0x2000
	v_mov_b32_e32 v1, s2
	global_atomic_add v0, v1, s[8:9] offset:1024

; __device__ __forceinline__ unsigned xb_ld(unsigned* p)              { return __hip_atomic_load(p, __ATOMIC_RELAXED, __HIP_MEMORY_SCOPE_AGENT); }
; __device__ __forceinline__ unsigned xb_add(unsigned* p, unsigned v) { return __hip_atomic_fetch_add(p, v, __ATOMIC_RELAXED, __HIP_MEMORY_SCOPE_AGENT); }
; #define XB_SPIN(cond, bar) do { unsigned _sp = 0; while (cond) { __builtin_amdgcn_s_sleep(1); \
;     if ((++_sp & 255u) == 0u) { if (xb_ld(&(bar)[XB_TMO])) break; if (_sp > XB_SPIN_CAP) { atomicAdd(&(bar)[XB_TMO], 1u); break; } } } } while (0)
; __device__ __forceinline__ void xcd_barrier(const XcdBarrier& b) {
;     ...
;         const unsigned old = xb_add(&bar[XB_XSUB(b.x)], 1u);
;         const unsigned gen = old / nloc;
;         if (old + 1u == (gen + 1u) * nloc) {
;             __builtin_amdgcn_fence(__ATOMIC_RELEASE, "agent");
;             asm volatile("s_waitcnt vmcnt(0)" ::: "memory");
;             const unsigned og = xb_add(&bar[XB_TOP], 1u);
;             const unsigned tg = og / nx;
;             if (og + 1u == (tg + 1u) * nx) xb_add(&bar[XB_TOPGEN], 1u);
;             else XB_SPIN(xb_ld(&bar[XB_TOPGEN]) == tg, bar);
;             __builtin_amdgcn_fence(__ATOMIC_ACQUIRE, "agent");
;             xb_add(&bar[XB_XGEN(b.x)], 1u);
;             asm volatile("s_waitcnt vmcnt(0)" ::: "memory");
;         } else {
;             XB_SPIN(xb_ld(&bar[XB_XGEN(b.x)]) == gen, bar);
.LBB0_1429:
	s_or_b64 exec, exec, s[10:11]
	v_cvt_f32_u32_e32 v4, v2
	s_waitcnt vmcnt(0)
	v_readfirstlane_b32 s2, v3
	v_sub_u32_e32 v3, 0, v2
	v_rcp_iflag_f32_e32 v4, v4
	v_add_u32_e32 v5, s2, v1
	v_mul_f32_e32 v4, 0x4f7ffffe, v4
	v_cvt_u32_f32_e32 v4, v4
	v_mul_lo_u32 v1, v3, v4
	v_mul_hi_u32 v1, v4, v1
	v_add_u32_e32 v1, v4, v1
	v_mul_hi_u32 v1, v5, v1
	v_mul_lo_u32 v3, v1, v2
	v_sub_u32_e32 v3, v5, v3
	v_add_u32_e32 v4, 1, v1
	v_cmp_ge_u32_e32 vcc, v3, v2
	s_nop 1
	v_cndmask_b32_e32 v1, v1, v4, vcc
	v_sub_u32_e32 v4, v3, v2
	v_cndmask_b32_e32 v3, v3, v4, vcc
	v_add_u32_e32 v4, 1, v1
	v_cmp_ge_u32_e32 vcc, v3, v2
	v_add_u32_e32 v3, 1, v5
	s_nop 0
	v_cndmask_b32_e32 v1, v1, v4, vcc
	v_mul_lo_u32 v4, v2, v1
	v_add_u32_e32 v2, v4, v2
	v_cmp_ne_u32_e32 vcc, v3, v2
	s_and_saveexec_b64 s[6:7], vcc
	s_xor_b64 s[8:9], exec, s[6:7]
	s_cbranch_execz .LBB0_1443
	buffer_inv sc1
	s_waitcnt lgkmcnt(0)
	v_mov_b32_e32 v0, 0x2000
	global_load_dword v0, v0, s[4:5] offset:1024 sc1
	s_add_u32 s14, s4, 0x2400
	s_addc_u32 s15, s5, 0
	s_waitcnt vmcnt(0)
	v_cmp_eq_u32_e32 vcc, v0, v1
	s_and_saveexec_b64 s[10:11], vcc
	s_cbranch_execz .LBB0_1442
	s_add_u32 s12, s70, 0x50200
	s_addc_u32 s13, s71, 0
	s_mov_b32 s3, 1
	s_mov_b64 s[30:31], 0
	v_mov_b32_e32 v0, 0
	s_branch .LBB0_1433

; __device__ __forceinline__ unsigned xb_ld(unsigned* p)              { return __hip_atomic_load(p, __ATOMIC_RELAXED, __HIP_MEMORY_SCOPE_AGENT); }
; __device__ __forceinline__ unsigned xb_add(unsigned* p, unsigned v) { return __hip_atomic_fetch_add(p, v, __ATOMIC_RELAXED, __HIP_MEMORY_SCOPE_AGENT); }
; #define XB_SPIN(cond, bar) do { unsigned _sp = 0; while (cond) { __builtin_amdgcn_s_sleep(1); \
;     if ((++_sp & 255u) == 0u) { if (xb_ld(&(bar)[XB_TMO])) break; if (_sp > XB_SPIN_CAP) { atomicAdd(&(bar)[XB_TMO], 1u); break; } } } } while (0)
; __device__ __forceinline__ void xcd_barrier(const XcdBarrier& b) {
;     ...
;         const unsigned old = xb_add(&bar[XB_XSUB(b.x)], 1u);
;         const unsigned gen = old / nloc;
;         if (old + 1u == (gen + 1u) * nloc) {
;             __builtin_amdgcn_fence(__ATOMIC_RELEASE, "agent");
;             asm volatile("s_waitcnt vmcnt(0)" ::: "memory");
;             const unsigned og = xb_add(&bar[XB_TOP], 1u);
;             const unsigned tg = og / nx;
;             if (og + 1u == (tg + 1u) * nx) xb_add(&bar[XB_TOPGEN], 1u);
;             else XB_SPIN(xb_ld(&bar[XB_TOPGEN]) == tg, bar);
;             __builtin_amdgcn_fence(__ATOMIC_ACQUIRE, "agent");
;             xb_add(&bar[XB_XGEN(b.x)], 1u);
;             asm volatile("s_waitcnt vmcnt(0)" ::: "memory");
;         } else {
;             XB_SPIN(xb_ld(&bar[XB_XGEN(b.x)]) == gen, bar);
.LBB0_1654:
	s_or_b64 exec, exec, s[10:11]
	v_cvt_f32_u32_e32 v4, v2
	s_waitcnt vmcnt(0)
	v_readfirstlane_b32 s2, v3
	v_sub_u32_e32 v3, 0, v2
	v_rcp_iflag_f32_e32 v4, v4
	v_add_u32_e32 v5, s2, v1
	v_mul_f32_e32 v4, 0x4f7ffffe, v4
	v_cvt_u32_f32_e32 v4, v4
	v_mul_lo_u32 v1, v3, v4
	v_mul_hi_u32 v1, v4, v1
	v_add_u32_e32 v1, v4, v1
	v_mul_hi_u32 v1, v5, v1
	v_mul_lo_u32 v3, v1, v2
	v_sub_u32_e32 v3, v5, v3
	v_add_u32_e32 v4, 1, v1
	v_cmp_ge_u32_e32 vcc, v3, v2
	s_nop 1
	v_cndmask_b32_e32 v1, v1, v4, vcc
	v_sub_u32_e32 v4, v3, v2
	v_cndmask_b32_e32 v3, v3, v4, vcc
	v_add_u32_e32 v4, 1, v1
	v_cmp_ge_u32_e32 vcc, v3, v2
	v_add_u32_e32 v3, 1, v5
	s_nop 0
	v_cndmask_b32_e32 v1, v1, v4, vcc
	v_mul_lo_u32 v4, v2, v1
	v_add_u32_e32 v2, v4, v2
	v_cmp_ne_u32_e32 vcc, v3, v2
	s_and_saveexec_b64 s[6:7], vcc
	s_xor_b64 s[8:9], exec, s[6:7]
	s_cbranch_execz .LBB0_1668
	buffer_inv sc1
	s_waitcnt lgkmcnt(0)
	v_mov_b32_e32 v0, 0x2000
	global_load_dword v0, v0, s[4:5] offset:1024 sc1
	s_add_u32 s14, s4, 0x2400
	s_addc_u32 s15, s5, 0
	s_waitcnt vmcnt(0)
	v_cmp_eq_u32_e32 vcc, v0, v1
	s_and_saveexec_b64 s[10:11], vcc
	s_cbranch_execz .LBB0_1667
	s_add_u32 s12, s70, 0x50200
	s_addc_u32 s13, s71, 0
	s_mov_b32 s3, 1
	s_mov_b64 s[20:21], 0
	v_mov_b32_e32 v0, 0
	s_branch .LBB0_1658

; __device__ __forceinline__ unsigned xb_ld(unsigned* p)              { return __hip_atomic_load(p, __ATOMIC_RELAXED, __HIP_MEMORY_SCOPE_AGENT); }
; __device__ __forceinline__ unsigned xb_add(unsigned* p, unsigned v) { return __hip_atomic_fetch_add(p, v, __ATOMIC_RELAXED, __HIP_MEMORY_SCOPE_AGENT); }
; #define XB_SPIN(cond, bar) do { unsigned _sp = 0; while (cond) { __builtin_amdgcn_s_sleep(1); \
;     if ((++_sp & 255u) == 0u) { if (xb_ld(&(bar)[XB_TMO])) break; if (_sp > XB_SPIN_CAP) { atomicAdd(&(bar)[XB_TMO], 1u); break; } } } } while (0)
; __device__ __forceinline__ void xcd_barrier(const XcdBarrier& b) {
;     ...
;         const unsigned old = xb_add(&bar[XB_XSUB(b.x)], 1u);
;         const unsigned gen = old / nloc;
;         if (old + 1u == (gen + 1u) * nloc) {
;             __builtin_amdgcn_fence(__ATOMIC_RELEASE, "agent");
;             asm volatile("s_waitcnt vmcnt(0)" ::: "memory");
;             const unsigned og = xb_add(&bar[XB_TOP], 1u);
;             const unsigned tg = og / nx;
;             if (og + 1u == (tg + 1u) * nx) xb_add(&bar[XB_TOPGEN], 1u);
;             else XB_SPIN(xb_ld(&bar[XB_TOPGEN]) == tg, bar);
;             __builtin_amdgcn_fence(__ATOMIC_ACQUIRE, "agent");
;             xb_add(&bar[XB_XGEN(b.x)], 1u);
;             asm volatile("s_waitcnt vmcnt(0)" ::: "memory");
;         } else {
;             XB_SPIN(xb_ld(&bar[XB_XGEN(b.x)]) == gen, bar);
.LBB0_1712:
	s_or_b64 exec, exec, s[10:11]
	v_cvt_f32_u32_e32 v4, v2
	s_waitcnt vmcnt(0)
	v_readfirstlane_b32 s2, v3
	v_sub_u32_e32 v3, 0, v2
	v_rcp_iflag_f32_e32 v4, v4
	v_add_u32_e32 v5, s2, v1
	v_mul_f32_e32 v4, 0x4f7ffffe, v4
	v_cvt_u32_f32_e32 v4, v4
	v_mul_lo_u32 v1, v3, v4
	v_mul_hi_u32 v1, v4, v1
	v_add_u32_e32 v1, v4, v1
	v_mul_hi_u32 v1, v5, v1
	v_mul_lo_u32 v3, v1, v2
	v_sub_u32_e32 v3, v5, v3
	v_add_u32_e32 v4, 1, v1
	v_cmp_ge_u32_e32 vcc, v3, v2
	s_nop 1
	v_cndmask_b32_e32 v1, v1, v4, vcc
	v_sub_u32_e32 v4, v3, v2
	v_cndmask_b32_e32 v3, v3, v4, vcc
	v_add_u32_e32 v4, 1, v1
	v_cmp_ge_u32_e32 vcc, v3, v2
	v_add_u32_e32 v3, 1, v5
	s_nop 0
	v_cndmask_b32_e32 v1, v1, v4, vcc
	v_mul_lo_u32 v4, v2, v1
	v_add_u32_e32 v2, v4, v2
	v_cmp_ne_u32_e32 vcc, v3, v2
	s_and_saveexec_b64 s[6:7], vcc
	s_xor_b64 s[8:9], exec, s[6:7]
	s_cbranch_execz .LBB0_1726
	buffer_inv sc1
	s_waitcnt lgkmcnt(0)
	v_mov_b32_e32 v0, 0x2000
	global_load_dword v0, v0, s[4:5] offset:1024 sc1
	s_add_u32 s14, s4, 0x2400
	s_addc_u32 s15, s5, 0
	s_waitcnt vmcnt(0)
	v_cmp_eq_u32_e32 vcc, v0, v1
	s_and_saveexec_b64 s[10:11], vcc
	s_cbranch_execz .LBB0_1725
	s_add_u32 s12, s70, 0x50200
	s_addc_u32 s13, s71, 0
	s_mov_b32 s3, 1
	s_mov_b64 s[16:17], 0
	v_mov_b32_e32 v0, 0
	s_branch .LBB0_1716

; __device__ __forceinline__ unsigned xb_ld(unsigned* p)              { return __hip_atomic_load(p, __ATOMIC_RELAXED, __HIP_MEMORY_SCOPE_AGENT); }
; __device__ __forceinline__ unsigned xb_add(unsigned* p, unsigned v) { return __hip_atomic_fetch_add(p, v, __ATOMIC_RELAXED, __HIP_MEMORY_SCOPE_AGENT); }
; #define XB_SPIN(cond, bar) do { unsigned _sp = 0; while (cond) { __builtin_amdgcn_s_sleep(1); \
;     if ((++_sp & 255u) == 0u) { if (xb_ld(&(bar)[XB_TMO])) break; if (_sp > XB_SPIN_CAP) { atomicAdd(&(bar)[XB_TMO], 1u); break; } } } } while (0)
; __device__ __forceinline__ void xcd_barrier(const XcdBarrier& b) {
;     ...
;         const unsigned old = xb_add(&bar[XB_XSUB(b.x)], 1u);
;         const unsigned gen = old / nloc;
;         if (old + 1u == (gen + 1u) * nloc) {
;             __builtin_amdgcn_fence(__ATOMIC_RELEASE, "agent");
;             asm volatile("s_waitcnt vmcnt(0)" ::: "memory");
;             const unsigned og = xb_add(&bar[XB_TOP], 1u);
;             const unsigned tg = og / nx;
;             if (og + 1u == (tg + 1u) * nx) xb_add(&bar[XB_TOPGEN], 1u);
;             else XB_SPIN(xb_ld(&bar[XB_TOPGEN]) == tg, bar);
;             __builtin_amdgcn_fence(__ATOMIC_ACQUIRE, "agent");
;             xb_add(&bar[XB_XGEN(b.x)], 1u);
;             asm volatile("s_waitcnt vmcnt(0)" ::: "memory");
;         } else {
;             XB_SPIN(xb_ld(&bar[XB_XGEN(b.x)]) == gen, bar);
.LBB0_2077:
	s_or_b64 exec, exec, s[6:7]
	v_cvt_f32_u32_e32 v4, v2
	s_waitcnt vmcnt(0)
	v_readfirstlane_b32 s4, v3
	v_sub_u32_e32 v3, 0, v2
	v_rcp_iflag_f32_e32 v4, v4
	v_add_u32_e32 v5, s4, v1
	v_mul_f32_e32 v4, 0x4f7ffffe, v4
	v_cvt_u32_f32_e32 v4, v4
	v_mul_lo_u32 v1, v3, v4
	v_mul_hi_u32 v1, v4, v1
	v_add_u32_e32 v1, v4, v1
	v_mul_hi_u32 v1, v5, v1
	v_mul_lo_u32 v3, v1, v2
	v_sub_u32_e32 v3, v5, v3
	v_add_u32_e32 v4, 1, v1
	v_cmp_ge_u32_e32 vcc, v3, v2
	s_nop 1
	v_cndmask_b32_e32 v1, v1, v4, vcc
	v_sub_u32_e32 v4, v3, v2
	v_cndmask_b32_e32 v3, v3, v4, vcc
	v_add_u32_e32 v4, 1, v1
	v_cmp_ge_u32_e32 vcc, v3, v2
	v_add_u32_e32 v3, 1, v5
	s_nop 0
	v_cndmask_b32_e32 v1, v1, v4, vcc
	v_mul_lo_u32 v4, v2, v1
	v_add_u32_e32 v2, v4, v2
	v_cmp_ne_u32_e32 vcc, v3, v2
	s_and_saveexec_b64 s[4:5], vcc
	s_xor_b64 s[4:5], exec, s[4:5]
	s_cbranch_execz .LBB0_2091
	buffer_inv sc1
	s_waitcnt lgkmcnt(0)
	v_mov_b32_e32 v0, 0x2000
	global_load_dword v0, v0, s[2:3] offset:1024 sc1
	s_add_u32 s10, s2, 0x2400
	s_addc_u32 s11, s3, 0
	s_waitcnt vmcnt(0)
	v_cmp_eq_u32_e32 vcc, v0, v1
	s_and_saveexec_b64 s[6:7], vcc
	s_cbranch_execz .LBB0_2090
	s_add_u32 s8, s70, 0x50200
	s_addc_u32 s9, s71, 0
	s_mov_b32 s22, 1
	s_mov_b64 s[12:13], 0
	v_mov_b32_e32 v0, 0
	s_branch .LBB0_2081

; __device__ __forceinline__ unsigned xb_ld(unsigned* p)              { return __hip_atomic_load(p, __ATOMIC_RELAXED, __HIP_MEMORY_SCOPE_AGENT); }
; #define XB_SPIN(cond, bar) do { unsigned _sp = 0; while (cond) { __builtin_amdgcn_s_sleep(1); \
;     if ((++_sp & 255u) == 0u) { if (xb_ld(&(bar)[XB_TMO])) break; if (_sp > XB_SPIN_CAP) { atomicAdd(&(bar)[XB_TMO], 1u); break; } } } } while (0)
; __device__ __forceinline__ void xcd_barrier(const XcdBarrier& b) {
;     ...
;             XB_SPIN(xb_ld(&bar[XB_XGEN(b.x)]) == gen, bar);
;             __builtin_amdgcn_fence(__ATOMIC_ACQUIRE, "agent");
;             asm volatile("s_waitcnt vmcnt(0)" ::: "memory");
.LBB0_2090:
	s_or_b64 exec, exec, s[6:7]
	s_waitcnt vmcnt(0)
	s_waitcnt vmcnt(0)

; __device__ __forceinline__ unsigned xb_add(unsigned* p, unsigned v) { return __hip_atomic_fetch_add(p, v, __ATOMIC_RELAXED, __HIP_MEMORY_SCOPE_AGENT); }
; __device__ __forceinline__ void xcd_barrier(const XcdBarrier& b) {
;     ...
;             __builtin_amdgcn_fence(__ATOMIC_ACQUIRE, "agent");
;             xb_add(&bar[XB_XGEN(b.x)], 1u);
;             asm volatile("s_waitcnt vmcnt(0)" ::: "memory");
.LBB0_2108:
	s_or_b64 exec, exec, s[4:5]
	s_mov_b64 s[4:5], exec
	v_mbcnt_lo_u32_b32 v0, s4, 0
	v_mbcnt_hi_u32_b32 v0, s5, v0
	v_cmp_eq_u32_e32 vcc, 0, v0
	s_waitcnt vmcnt(0)
	buffer_inv sc1
	s_waitcnt vmcnt(0)
	s_and_saveexec_b64 s[6:7], vcc
	s_cbranch_execz .LBB0_2110
	s_bcnt1_i32_b64 s4, s[4:5]
	v_mov_b32_e32 v0, 0x2000
	v_mov_b32_e32 v1, s4
	global_atomic_add v0, v1, s[2:3] offset:1024
